# sub-grid barrier wait after a sample-side arrival: first poll and L1 invalidate requested before the arrival's counter add (10 sites)
# speedup vs baseline: 1.0055x; 1.0055x over previous
.LBB11_480:
	s_or_b64 exec, exec, s[10:11]
	s_barrier
	s_getreg_b32 s0, hwreg(HW_REG_XCC_ID, 0, 4)
	s_waitcnt vmcnt(0)
	s_barrier
	s_mov_b64 s[6:7], exec
	v_readlane_b32 s8, v248, 2
	v_readlane_b32 s9, v248, 3
	s_and_b64 s[8:9], s[6:7], s[8:9]
	s_xor_b64 s[10:11], s[8:9], s[6:7]
	s_mov_b64 exec, s[8:9]
	s_getreg_b32 s1, hwreg(HW_REG_XCC_ID, 0, 4)
	s_andn2_saveexec_b64 s[10:11], s[10:11]
	s_cbranch_execz .LBB11_568
	v_readlane_b32 s1, v242, 36
	s_waitcnt vmcnt(0) expcnt(0) lgkmcnt(0)
	s_getreg_b32 s100, hwreg(HW_REG_XCC_ID, 0, 4)
	s_and_b32 s100, s100, 15
	s_lshl_b32 s100, s100, 8
	s_add_u32 s100, s74, s100
	s_addc_u32 s101, s75, 0
	buffer_inv sc1
	global_load_dword v255, v207, s[100:101] offset:1024 sc1
	s_and_b32 s6, s0, 15
	v_mov_b32_e32 v0, s1
	ds_read_b32 v2, v0
	v_readlane_b32 s1, v242, 35
	s_waitcnt lgkmcnt(0)
	v_cmp_ne_u32_e32 vcc, 0, v2
	v_mov_b32_e32 v0, s1
	ds_read_b32 v0, v0
	s_cbranch_vccnz .LBB11_498
	s_mov_b32 s0, 1
	s_branch .LBB11_486

.LBB11_553:
	s_and_b64 vcc, exec, s[18:19]
	s_cbranch_vccz .LBB11_568
	v_readlane_b32 s1, v242, 31
	s_lshl_b32 s0, s0, 8
	s_add_u32 s0, s74, s0
	v_mov_b32_e32 v2, s1
	ds_read_b32 v2, v2
	s_addc_u32 s1, s75, 0
	s_add_u32 s18, s0, 0x1400
	s_addc_u32 s19, s1, 0
	s_waitcnt lgkmcnt(0)
	v_mul_lo_u32 v0, v2, v0
	v_mov_b32_e32 v2, v255
	s_waitcnt vmcnt(0)
	v_cmp_ge_u32_e32 vcc, v2, v0
	s_cbranch_vccnz .LBB11_567
	s_mov_b32 s0, 1
	s_branch .LBB11_557

.LBB11_825:
	s_getreg_b32 s0, hwreg(HW_REG_XCC_ID, 0, 4)
	s_waitcnt vmcnt(0)
	s_waitcnt lgkmcnt(0)
	s_barrier
	s_mov_b64 s[6:7], exec
	v_readlane_b32 s8, v248, 2
	v_readlane_b32 s9, v248, 3
	s_and_b64 s[8:9], s[6:7], s[8:9]
	s_xor_b64 s[10:11], s[8:9], s[6:7]
	s_mov_b64 exec, s[8:9]
	s_getreg_b32 s1, hwreg(HW_REG_XCC_ID, 0, 4)
	s_or_saveexec_b64 s[10:11], s[10:11]
	v_readlane_b32 s50, v242, 52
	v_readlane_b32 s51, v242, 53
	v_readlane_b32 s44, v242, 54
	s_mov_b32 s34, s70
	v_readlane_b32 s45, v242, 55
	s_xor_b64 exec, exec, s[10:11]
	s_cbranch_execz .LBB11_913
	v_readlane_b32 s1, v242, 36
	s_waitcnt vmcnt(0) expcnt(0) lgkmcnt(0)
	s_getreg_b32 s100, hwreg(HW_REG_XCC_ID, 0, 4)
	s_and_b32 s100, s100, 15
	s_lshl_b32 s100, s100, 8
	s_add_u32 s100, s74, s100
	s_addc_u32 s101, s75, 0
	buffer_inv sc1
	global_load_dword v255, v207, s[100:101] offset:1024 sc1
	s_and_b32 s6, s0, 15
	v_mov_b32_e32 v0, s1
	ds_read_b32 v2, v0
	v_readlane_b32 s1, v242, 35
	s_waitcnt lgkmcnt(0)
	v_cmp_ne_u32_e32 vcc, 0, v2
	v_mov_b32_e32 v0, s1
	ds_read_b32 v0, v0
	s_cbranch_vccnz .LBB11_843
	s_mov_b32 s0, 1
	s_branch .LBB11_831

.LBB11_898:
	s_and_b64 vcc, exec, s[12:13]
	s_cbranch_vccz .LBB11_913
	v_readlane_b32 s1, v242, 31
	s_lshl_b32 s0, s0, 8
	s_add_u32 s0, s74, s0
	v_mov_b32_e32 v2, s1
	ds_read_b32 v2, v2
	s_addc_u32 s1, s75, 0
	s_add_u32 s12, s0, 0x1400
	s_addc_u32 s13, s1, 0
	s_waitcnt lgkmcnt(0)
	v_mul_lo_u32 v0, v2, v0
	v_mov_b32_e32 v2, v255
	s_waitcnt vmcnt(0)
	v_cmp_ge_u32_e32 vcc, v2, v0
	s_cbranch_vccnz .LBB11_912
	s_mov_b32 s0, 1
	s_branch .LBB11_902

.LBB11_1063:
	s_waitcnt lgkmcnt(0)
	s_barrier
	s_getreg_b32 s0, hwreg(HW_REG_XCC_ID, 0, 4)
	s_waitcnt vmcnt(0)
	s_barrier
	s_mov_b64 s[6:7], exec
	v_readlane_b32 s8, v248, 2
	v_readlane_b32 s9, v248, 3
	s_and_b64 s[8:9], s[6:7], s[8:9]
	s_xor_b64 s[10:11], s[8:9], s[6:7]
	s_mov_b64 exec, s[8:9]
	s_getreg_b32 s1, hwreg(HW_REG_XCC_ID, 0, 4)
	s_andn2_saveexec_b64 s[10:11], s[10:11]
	s_cbranch_execz .LBB11_1151
	v_readlane_b32 s1, v242, 36
	s_waitcnt vmcnt(0) expcnt(0) lgkmcnt(0)
	s_getreg_b32 s100, hwreg(HW_REG_XCC_ID, 0, 4)
	s_and_b32 s100, s100, 15
	s_lshl_b32 s100, s100, 8
	s_add_u32 s100, s74, s100
	s_addc_u32 s101, s75, 0
	buffer_inv sc1
	global_load_dword v255, v207, s[100:101] offset:1024 sc1
	s_and_b32 s6, s0, 15
	v_mov_b32_e32 v0, s1
	ds_read_b32 v2, v0
	v_readlane_b32 s1, v242, 35
	s_waitcnt lgkmcnt(0)
	v_cmp_ne_u32_e32 vcc, 0, v2
	v_mov_b32_e32 v0, s1
	ds_read_b32 v0, v0
	s_cbranch_vccnz .LBB11_1081
	s_mov_b32 s0, 1
	s_branch .LBB11_1069

.LBB11_1343:
	s_waitcnt lgkmcnt(0)
	s_barrier
	s_getreg_b32 s0, hwreg(HW_REG_XCC_ID, 0, 4)
	s_waitcnt vmcnt(0)
	s_barrier
	s_mov_b64 s[6:7], exec
	v_readlane_b32 s8, v248, 2
	v_readlane_b32 s9, v248, 3
	s_and_b64 s[8:9], s[6:7], s[8:9]
	s_xor_b64 s[12:13], s[8:9], s[6:7]
	s_mov_b64 exec, s[8:9]
	s_getreg_b32 s1, hwreg(HW_REG_XCC_ID, 0, 4)
	s_andn2_saveexec_b64 s[12:13], s[12:13]
	s_cbranch_execz .LBB11_1431
	v_readlane_b32 s1, v242, 36
	s_waitcnt vmcnt(0) expcnt(0) lgkmcnt(0)
	s_getreg_b32 s100, hwreg(HW_REG_XCC_ID, 0, 4)
	s_and_b32 s100, s100, 15
	s_lshl_b32 s100, s100, 8
	s_add_u32 s100, s74, s100
	s_addc_u32 s101, s75, 0
	buffer_inv sc1
	global_load_dword v255, v207, s[100:101] offset:1024 sc1
	s_and_b32 s6, s0, 15
	v_mov_b32_e32 v0, s1
	ds_read_b32 v2, v0
	v_readlane_b32 s1, v242, 35
	s_waitcnt lgkmcnt(0)
	v_cmp_ne_u32_e32 vcc, 0, v2
	v_mov_b32_e32 v0, s1
	ds_read_b32 v0, v0
	s_cbranch_vccnz .LBB11_1361
	s_mov_b32 s0, 1
	s_branch .LBB11_1349

.LBB11_1416:
	s_and_b64 vcc, exec, s[14:15]
	s_cbranch_vccz .LBB11_1431
	v_readlane_b32 s1, v242, 31
	s_lshl_b32 s0, s0, 8
	s_add_u32 s0, s74, s0
	v_mov_b32_e32 v2, s1
	ds_read_b32 v2, v2
	s_addc_u32 s1, s75, 0
	s_add_u32 s14, s0, 0x1400
	s_addc_u32 s15, s1, 0
	s_waitcnt lgkmcnt(0)
	v_mul_lo_u32 v0, v2, v0
	v_mov_b32_e32 v2, v255
	s_waitcnt vmcnt(0)
	v_cmp_ge_u32_e32 vcc, v2, v0
	s_cbranch_vccnz .LBB11_1430
	s_mov_b32 s0, 1
	s_branch .LBB11_1420

.LBB11_1528:
	s_getreg_b32 s0, hwreg(HW_REG_XCC_ID, 0, 4)
	s_waitcnt vmcnt(0)
	s_barrier
	s_mov_b64 s[6:7], exec
	v_readlane_b32 s8, v248, 2
	v_readlane_b32 s9, v248, 3
	s_and_b64 s[8:9], s[6:7], s[8:9]
	s_xor_b64 s[10:11], s[8:9], s[6:7]
	s_mov_b64 exec, s[8:9]
	s_getreg_b32 s1, hwreg(HW_REG_XCC_ID, 0, 4)
	s_or_saveexec_b64 s[10:11], s[10:11]
	v_readlane_b32 s44, v242, 54
	v_readlane_b32 s45, v242, 55
	s_xor_b64 exec, exec, s[10:11]
	s_cbranch_execz .LBB11_1616
	v_readlane_b32 s1, v242, 36
	s_waitcnt vmcnt(0) expcnt(0) lgkmcnt(0)
	s_getreg_b32 s100, hwreg(HW_REG_XCC_ID, 0, 4)
	s_and_b32 s100, s100, 15
	s_lshl_b32 s100, s100, 8
	s_add_u32 s100, s74, s100
	s_addc_u32 s101, s75, 0
	buffer_inv sc1
	global_load_dword v255, v207, s[100:101] offset:1024 sc1
	s_and_b32 s6, s0, 15
	v_mov_b32_e32 v0, s1
	ds_read_b32 v2, v0
	v_readlane_b32 s1, v242, 35
	s_waitcnt lgkmcnt(0)
	v_cmp_ne_u32_e32 vcc, 0, v2
	v_mov_b32_e32 v0, s1
	ds_read_b32 v0, v0
	s_cbranch_vccnz .LBB11_1546
	s_mov_b32 s0, 1
	s_branch .LBB11_1534

.LBB11_2228:
	s_getreg_b32 s0, hwreg(HW_REG_XCC_ID, 0, 4)
	s_waitcnt vmcnt(0)
	s_barrier
	s_mov_b64 s[6:7], exec
	v_readlane_b32 s8, v248, 2
	v_readlane_b32 s9, v248, 3
	s_and_b64 s[8:9], s[6:7], s[8:9]
	s_xor_b64 s[10:11], s[8:9], s[6:7]
	s_mov_b64 exec, s[8:9]
	s_getreg_b32 s1, hwreg(HW_REG_XCC_ID, 0, 4)
	s_andn2_saveexec_b64 s[12:13], s[10:11]
	s_cbranch_execz .LBB11_2316
	v_readlane_b32 s1, v242, 36
	s_waitcnt vmcnt(0) expcnt(0) lgkmcnt(0)
	s_getreg_b32 s100, hwreg(HW_REG_XCC_ID, 0, 4)
	s_and_b32 s100, s100, 15
	s_lshl_b32 s100, s100, 8
	s_add_u32 s100, s74, s100
	s_addc_u32 s101, s75, 0
	buffer_inv sc1
	global_load_dword v255, v207, s[100:101] offset:1024 sc1
	s_and_b32 s6, s0, 15
	v_mov_b32_e32 v0, s1
	ds_read_b32 v2, v0
	v_readlane_b32 s1, v242, 35
	s_waitcnt lgkmcnt(0)
	v_cmp_ne_u32_e32 vcc, 0, v2
	v_mov_b32_e32 v0, s1
	ds_read_b32 v0, v0
	s_cbranch_vccnz .LBB11_2246
	s_mov_b32 s0, 1
	s_branch .LBB11_2234

.LBB11_2301:
	s_and_b64 vcc, exec, s[10:11]
	s_cbranch_vccz .LBB11_2316
	v_readlane_b32 s1, v242, 31
	s_lshl_b32 s0, s0, 8
	s_add_u32 s0, s74, s0
	v_mov_b32_e32 v2, s1
	ds_read_b32 v2, v2
	s_addc_u32 s1, s75, 0
	s_add_u32 s10, s0, 0x1400
	s_addc_u32 s11, s1, 0
	s_waitcnt lgkmcnt(0)
	v_mul_lo_u32 v0, v2, v0
	v_mov_b32_e32 v2, v255
	s_waitcnt vmcnt(0)
	v_cmp_ge_u32_e32 vcc, v2, v0
	s_cbranch_vccnz .LBB11_2315
	s_mov_b32 s0, 1
	s_branch .LBB11_2305

.LBB11_2669:
	s_barrier
	s_getreg_b32 s0, hwreg(HW_REG_XCC_ID, 0, 4)
	s_waitcnt vmcnt(0)
	s_barrier
	s_mov_b64 s[6:7], exec
	v_readlane_b32 s8, v248, 2
	v_readlane_b32 s9, v248, 3
	s_and_b64 s[8:9], s[6:7], s[8:9]
	s_xor_b64 s[10:11], s[8:9], s[6:7]
	s_mov_b64 exec, s[8:9]
	s_getreg_b32 s1, hwreg(HW_REG_XCC_ID, 0, 4)
	s_andn2_saveexec_b64 s[10:11], s[10:11]
	s_cbranch_execz .LBB11_2757
	v_readlane_b32 s1, v242, 36
	s_waitcnt vmcnt(0) expcnt(0) lgkmcnt(0)
	s_getreg_b32 s100, hwreg(HW_REG_XCC_ID, 0, 4)
	s_and_b32 s100, s100, 15
	s_lshl_b32 s100, s100, 8
	s_add_u32 s100, s74, s100
	s_addc_u32 s101, s75, 0
	buffer_inv sc1
	global_load_dword v255, v207, s[100:101] offset:1024 sc1
	s_and_b32 s6, s0, 15
	v_mov_b32_e32 v0, s1
	ds_read_b32 v2, v0
	v_readlane_b32 s1, v242, 35
	s_waitcnt lgkmcnt(0)
	v_cmp_ne_u32_e32 vcc, 0, v2
	v_mov_b32_e32 v0, s1
	ds_read_b32 v0, v0
	s_cbranch_vccnz .LBB11_2687
	s_mov_b32 s0, 1
	s_branch .LBB11_2675

.LBB11_2921:
	v_readlane_b32 s1, v242, 36
	s_waitcnt vmcnt(0) expcnt(0) lgkmcnt(0)
	s_getreg_b32 s100, hwreg(HW_REG_XCC_ID, 0, 4)
	s_and_b32 s100, s100, 15
	s_lshl_b32 s100, s100, 8
	s_add_u32 s100, s74, s100
	s_addc_u32 s101, s75, 0
	buffer_inv sc1
	global_load_dword v255, v207, s[100:101] offset:1024 sc1
	s_and_b32 s6, s0, 15
	v_mov_b32_e32 v0, s1
	ds_read_b32 v2, v0
	v_readlane_b32 s1, v242, 35
	s_waitcnt lgkmcnt(0)
	v_cmp_ne_u32_e32 vcc, 0, v2
	v_mov_b32_e32 v0, s1
	ds_read_b32 v0, v0
	s_cbranch_vccnz .LBB11_2936
	s_mov_b32 s0, 1
	s_branch .LBB11_2924

.LBB11_2992:
	v_readlane_b32 s1, v242, 31
	s_lshl_b32 s0, s0, 8
	s_add_u32 s0, s74, s0
	v_mov_b32_e32 v2, s1
	ds_read_b32 v2, v2
	s_addc_u32 s1, s75, 0
	s_add_u32 s12, s0, 0x1400
	s_addc_u32 s13, s1, 0
	s_waitcnt lgkmcnt(0)
	v_mul_lo_u32 v0, v2, v0
	v_mov_b32_e32 v2, v255
	s_waitcnt vmcnt(0)
	v_cmp_ge_u32_e32 vcc, v2, v0
	s_cbranch_vccz .LBB11_2993
	s_getpc_b64 s[98:99]
